# QK-norm items: the eight steps' RoPE-table loads issued together at the top of the item (no per-step load-wait ladder)
# baseline (speedup 1.0000x reference)
.LBB0_311:
	v_mov_b32_e32 v72, v188
	s_nop 0
	v_and_b32_e32 v82, 7, v72
	v_lshlrev_b32_e32 v8, 5, v82
	global_load_dwordx4 v[0:3], v8, s[64:65] offset:16
	global_load_dwordx4 v[4:7], v8, s[64:65]
	v_ashrrev_i32_e32 v8, 6, v72
	v_add_u32_e32 v73, s14, v8
	v_lshlrev_b32_e32 v10, 4, v72
	v_mad_i64_i32 v[8:9], s[2:3], v73, s18, v[36:37]
	v_and_b32_e32 v38, 0x3f0, v10
	v_lshl_add_u64 v[54:55], v[8:9], 0, v[38:39]
	v_add_u32_e32 v71, 8, v73
	v_add_co_u32_e32 v8, vcc, s0, v54
	v_mad_i64_i32 v[10:11], s[2:3], v71, s18, v[36:37]
	s_nop 0
	v_addc_co_u32_e32 v9, vcc, 0, v55, vcc
	v_lshl_add_u64 v[52:53], v[10:11], 0, v[38:39]
	v_add_co_u32_e32 v10, vcc, s0, v52
	v_add_u32_e32 v70, 16, v73
	s_nop 0
	v_addc_co_u32_e32 v11, vcc, 0, v53, vcc
	global_load_dwordx4 v[56:59], v[8:9], off
	global_load_dwordx4 v[32:35], v[10:11], off
	v_mad_i64_i32 v[8:9], s[2:3], v70, s18, v[36:37]
	v_lshl_add_u64 v[50:51], v[8:9], 0, v[38:39]
	v_add_u32_e32 v69, 24, v73
	v_add_co_u32_e32 v8, vcc, s0, v50
	v_mad_i64_i32 v[10:11], s[2:3], v69, s18, v[36:37]
	s_nop 0
	v_addc_co_u32_e32 v9, vcc, 0, v51, vcc
	v_lshl_add_u64 v[48:49], v[10:11], 0, v[38:39]
	v_add_co_u32_e32 v10, vcc, s0, v48
	v_add_u32_e32 v68, 32, v73
	s_nop 0
	v_addc_co_u32_e32 v11, vcc, 0, v49, vcc
	global_load_dwordx4 v[28:31], v[8:9], off
	global_load_dwordx4 v[24:27], v[10:11], off
	v_mad_i64_i32 v[8:9], s[2:3], v68, s18, v[36:37]
	v_lshl_add_u64 v[46:47], v[8:9], 0, v[38:39]
	v_add_u32_e32 v67, 40, v73
	v_add_co_u32_e32 v8, vcc, s0, v46
	v_mad_i64_i32 v[10:11], s[2:3], v67, s18, v[36:37]
	s_nop 0
	v_addc_co_u32_e32 v9, vcc, 0, v47, vcc
	v_lshl_add_u64 v[44:45], v[10:11], 0, v[38:39]
	v_add_co_u32_e32 v10, vcc, s0, v44
	v_add_u32_e32 v66, 48, v73
	s_nop 0
	v_addc_co_u32_e32 v11, vcc, 0, v45, vcc
	global_load_dwordx4 v[20:23], v[8:9], off
	global_load_dwordx4 v[16:19], v[10:11], off
	v_mad_i64_i32 v[8:9], s[2:3], v66, s18, v[36:37]
	v_lshl_add_u64 v[42:43], v[8:9], 0, v[38:39]
	v_add_u32_e32 v65, 56, v73
	v_add_co_u32_e32 v60, vcc, s0, v42
	v_mad_i64_i32 v[8:9], s[2:3], v65, s18, v[36:37]
	s_nop 0
	v_addc_co_u32_e32 v61, vcc, 0, v43, vcc
	v_lshl_add_u64 v[40:41], v[8:9], 0, v[38:39]
	v_add_co_u32_e32 v62, vcc, s0, v40
	v_lshlrev_b32_e32 v38, 3, v72
	s_nop 0
	v_addc_co_u32_e32 v63, vcc, 0, v41, vcc
	global_load_dwordx4 v[12:15], v[60:61], off
	global_load_dwordx4 v[8:11], v[62:63], off
	v_and_b32_e32 v83, 8, v38
	v_cmp_gt_u32_e64 s[2:3], 4, v82
	v_and_b32_e32 v240, 1, v188
	v_lshlrev_b32_e32 v240, 6, v240
	v_and_b32_e32 v241, 63, v73
	v_bfe_u32 v242, v73, 6, 7
	v_cndmask_b32_e64 v241, v241, v242, s[2:3]
	v_lshl_or_b32 v232, v241, 7, v240
	global_load_dwordx4 v[100:103], v232, s[8:9]
	global_load_dwordx4 v[104:107], v232, s[8:9] offset:16
	global_load_dwordx4 v[108:111], v232, s[8:9] offset:32
	global_load_dwordx4 v[112:115], v232, s[8:9] offset:48
	v_and_b32_e32 v241, 63, v71
	v_bfe_u32 v242, v71, 6, 7
	v_cndmask_b32_e64 v241, v241, v242, s[2:3]
	v_lshl_or_b32 v233, v241, 7, v240
	global_load_dwordx4 v[116:119], v233, s[8:9]
	global_load_dwordx4 v[120:123], v233, s[8:9] offset:16
	global_load_dwordx4 v[124:127], v233, s[8:9] offset:32
	global_load_dwordx4 v[128:131], v233, s[8:9] offset:48
	v_and_b32_e32 v241, 63, v70
	v_bfe_u32 v242, v70, 6, 7
	v_cndmask_b32_e64 v241, v241, v242, s[2:3]
	v_lshl_or_b32 v234, v241, 7, v240
	global_load_dwordx4 v[132:135], v234, s[8:9]
	global_load_dwordx4 v[136:139], v234, s[8:9] offset:16
	global_load_dwordx4 v[140:143], v234, s[8:9] offset:32
	global_load_dwordx4 v[144:147], v234, s[8:9] offset:48
	v_and_b32_e32 v241, 63, v69
	v_bfe_u32 v242, v69, 6, 7
	v_cndmask_b32_e64 v241, v241, v242, s[2:3]
	v_lshl_or_b32 v235, v241, 7, v240
	global_load_dwordx4 v[148:151], v235, s[8:9]
	global_load_dwordx4 v[152:155], v235, s[8:9] offset:16
	global_load_dwordx4 v[156:159], v235, s[8:9] offset:32
	global_load_dwordx4 v[160:163], v235, s[8:9] offset:48
	v_and_b32_e32 v241, 63, v68
	v_bfe_u32 v242, v68, 6, 7
	v_cndmask_b32_e64 v241, v241, v242, s[2:3]
	v_lshl_or_b32 v236, v241, 7, v240
	global_load_dwordx4 v[164:167], v236, s[8:9]
	global_load_dwordx4 v[168:171], v236, s[8:9] offset:16
	global_load_dwordx4 v[172:175], v236, s[8:9] offset:32
	global_load_dwordx4 v[176:179], v236, s[8:9] offset:48
	v_and_b32_e32 v241, 63, v67
	v_bfe_u32 v242, v67, 6, 7
	v_cndmask_b32_e64 v241, v241, v242, s[2:3]
	v_lshl_or_b32 v237, v241, 7, v240
	global_load_dwordx4 v[180:183], v237, s[8:9]
	global_load_dwordx4 v[184:187], v237, s[8:9] offset:16
	global_load_dwordx4 v[192:195], v237, s[8:9] offset:32
	global_load_dwordx4 v[196:199], v237, s[8:9] offset:48
	v_and_b32_e32 v241, 63, v66
	v_bfe_u32 v242, v66, 6, 7
	v_cndmask_b32_e64 v241, v241, v242, s[2:3]
	v_lshl_or_b32 v238, v241, 7, v240
	global_load_dwordx4 v[200:203], v238, s[8:9]
	global_load_dwordx4 v[204:207], v238, s[8:9] offset:16
	global_load_dwordx4 v[208:211], v238, s[8:9] offset:32
	global_load_dwordx4 v[212:215], v238, s[8:9] offset:48
	v_and_b32_e32 v241, 63, v65
	v_bfe_u32 v242, v65, 6, 7
	v_cndmask_b32_e64 v241, v241, v242, s[2:3]
	v_lshl_or_b32 v239, v241, 7, v240
	global_load_dwordx4 v[216:219], v239, s[8:9]
	global_load_dwordx4 v[220:223], v239, s[8:9] offset:16
	global_load_dwordx4 v[224:227], v239, s[8:9] offset:32
	global_load_dwordx4 v[228:231], v239, s[8:9] offset:48
	s_waitcnt vmcnt(0)
	v_lshlrev_b32_e32 v60, 16, v56
	v_and_b32_e32 v61, 0xffff0000, v56
	v_pk_mul_f32 v[76:77], v[60:61], v[60:61]
	v_lshlrev_b32_e32 v56, 16, v57
	v_and_b32_e32 v57, 0xffff0000, v57
	v_pk_mul_f32 v[78:79], v[56:57], v[56:57]
	v_add_f32_e32 v38, v76, v77
	v_lshlrev_b32_e32 v80, 16, v58
	v_and_b32_e32 v81, 0xffff0000, v58
	v_add_f32_e32 v38, v78, v38
	v_and_b32_e32 v74, 0xffff0000, v59
	v_lshlrev_b32_e32 v75, 16, v59
	v_pk_mul_f32 v[58:59], v[80:81], v[80:81]
	v_add_f32_e32 v38, v79, v38
	v_add_f32_e32 v38, v58, v38
	v_pk_mul_f32 v[62:63], v[74:75], v[74:75]
	v_add_f32_e32 v38, v59, v38
	v_add_f32_e32 v38, v63, v38
	v_add_f32_e32 v38, v62, v38
	s_nop 1
	v_add_f32_dpp v38, v38, v38 quad_perm:[1,0,3,2] row_mask:0xf bank_mask:0xf bound_ctrl:1
	s_nop 1
	v_add_f32_dpp v38, v38, v38 quad_perm:[2,3,0,1] row_mask:0xf bank_mask:0xf bound_ctrl:1
	s_nop 1
	v_add_f32_dpp v38, v38, v38 row_half_mirror row_mask:0xf bank_mask:0xf bound_ctrl:1
	v_fmamk_f32 v38, v38, 0x3c800000, v64
	v_mul_f32_e32 v58, 0x4b800000, v38
	v_cmp_gt_f32_e64 s[4:5], s1, v38
	s_nop 1
	v_cndmask_b32_e64 v38, v38, v58, s[4:5]
	v_rsq_f32_e32 v38, v38
	v_and_b32_e32 v58, 2, v72
	v_cmp_eq_u32_e32 vcc, 0, v58
	v_mul_f32_e32 v58, 0x45800000, v38
	v_cndmask_b32_e64 v38, v38, v58, s[4:5]
	v_pk_mul_f32 v[58:59], v[38:39], v[60:61] op_sel_hi:[0,1]
	v_pk_mul_f32 v[56:57], v[38:39], v[56:57] op_sel_hi:[0,1]
	v_pk_mul_f32 v[60:61], v[4:5], v[58:59]
	v_pk_mul_f32 v[62:63], v[6:7], v[56:57]
	v_pk_mul_f32 v[56:57], v[38:39], v[80:81] op_sel_hi:[0,1]
	v_pk_mul_f32 v[58:59], v[38:39], v[74:75] op_sel_hi:[0,1]
	v_pk_mul_f32 v[56:57], v[0:1], v[56:57]
	v_pk_mul_f32 v[58:59], v[2:3], v[58:59] op_sel:[0,1] op_sel_hi:[1,0]
	v_cmp_gt_i32_e64 s[4:5], s19, v73
	v_lshlrev_b32_e32 v38, 3, v83
	s_and_saveexec_b64 s[12:13], s[4:5]
	s_cbranch_execz .LBB0_313
	v_mov_b32_e32 v72, v100
	v_mov_b32_e32 v73, v101
	v_mov_b32_e32 v74, v102
	v_mov_b32_e32 v75, v103
	v_mov_b32_e32 v76, v104
	v_mov_b32_e32 v77, v105
	v_mov_b32_e32 v78, v106
	v_mov_b32_e32 v79, v107
	v_mov_b32_e32 v80, v108
	v_mov_b32_e32 v81, v109
	v_mov_b32_e32 v82, v110
	v_mov_b32_e32 v83, v111
	v_mov_b32_e32 v84, v112
	v_mov_b32_e32 v85, v113
	v_mov_b32_e32 v86, v114
	v_mov_b32_e32 v87, v115
	v_mov_b32_e32 v88, v39
	v_mov_b32_e32 v89, v39
	v_mov_b32_e32 v90, v39
	v_mov_b32_e32 v91, v39
	v_mov_b32_e32 v92, v39
	v_mov_b32_e32 v93, v39
	v_mov_b32_e32 v94, v39
	v_mov_b32_e32 v95, v39
	v_mov_b32_dpp v88, v60 quad_perm:[2,3,0,1] row_mask:0xf bank_mask:0xf
	v_mov_b32_dpp v89, v61 quad_perm:[2,3,0,1] row_mask:0xf bank_mask:0xf
	v_mov_b32_dpp v90, v62 quad_perm:[2,3,0,1] row_mask:0xf bank_mask:0xf
	v_mov_b32_dpp v91, v63 quad_perm:[2,3,0,1] row_mask:0xf bank_mask:0xf
	v_mov_b32_dpp v92, v56 quad_perm:[2,3,0,1] row_mask:0xf bank_mask:0xf
	v_mov_b32_dpp v93, v57 quad_perm:[2,3,0,1] row_mask:0xf bank_mask:0xf
	v_mov_b32_dpp v94, v58 quad_perm:[2,3,0,1] row_mask:0xf bank_mask:0xf
	v_mov_b32_dpp v95, v59 quad_perm:[2,3,0,1] row_mask:0xf bank_mask:0xf
	v_mov_b32_e32 v97, v74
	v_mov_b32_e32 v74, v73
	v_mov_b32_e32 v73, v78
	v_mov_b32_e32 v78, v77
	v_mov_b32_e32 v77, v82
	v_mov_b32_e32 v82, v81
	v_mov_b32_e32 v81, v86
	v_mov_b32_e32 v86, v85
	v_mov_b32_e32 v96, v72
	v_mov_b32_e32 v72, v76
	v_mov_b32_e32 v76, v80
	v_mov_b32_e32 v80, v84
	v_pk_mul_f32 v[74:75], v[74:75], v[88:89]
	v_pk_mul_f32 v[78:79], v[78:79], v[90:91]
	v_pk_mul_f32 v[82:83], v[82:83], v[92:93]
	v_pk_mul_f32 v[84:85], v[86:87], v[94:95]
	v_cndmask_b32_e64 v75, v75, -v75, vcc
	v_cndmask_b32_e64 v74, v74, -v74, vcc
	v_cndmask_b32_e64 v79, v79, -v79, vcc
	v_cndmask_b32_e64 v78, v78, -v78, vcc
	v_cndmask_b32_e64 v83, v83, -v83, vcc
	v_cndmask_b32_e64 v82, v82, -v82, vcc
	v_cndmask_b32_e64 v85, v85, -v85, vcc
	v_cndmask_b32_e64 v84, v84, -v84, vcc
	v_pk_fma_f32 v[60:61], v[60:61], v[96:97], v[74:75]
	v_pk_fma_f32 v[62:63], v[62:63], v[72:73], v[78:79]
	v_pk_fma_f32 v[56:57], v[56:57], v[76:77], v[82:83]
	v_pk_fma_f32 v[58:59], v[58:59], v[80:81], v[84:85]
.LBB0_313:
	s_or_b64 exec, exec, s[12:13]
	v_lshlrev_b32_e32 v74, 16, v32
	v_and_b32_e32 v75, 0xffff0000, v32
	v_pk_mul_f32 v[76:77], v[74:75], v[74:75]
	v_lshlrev_b32_e32 v32, 16, v33
	v_and_b32_e32 v33, 0xffff0000, v33
	v_pk_mul_f32 v[78:79], v[32:33], v[32:33]
	v_add_f32_e32 v76, v76, v77
	v_lshlrev_b32_e32 v80, 16, v34
	v_and_b32_e32 v81, 0xffff0000, v34
	v_add_f32_e32 v76, v78, v76
	v_lshl_add_u64 v[72:73], v[54:55], 0, s[10:11]
	v_cvt_pk_bf16_f32 v54, v60, v61
	v_and_b32_e32 v60, 0xffff0000, v35
	v_lshlrev_b32_e32 v61, 16, v35
	v_pk_mul_f32 v[34:35], v[80:81], v[80:81]
	v_add_f32_e32 v76, v79, v76
	v_add_f32_e32 v34, v34, v76
	v_cvt_pk_bf16_f32 v55, v62, v63
	v_pk_mul_f32 v[62:63], v[60:61], v[60:61]
	v_add_f32_e32 v34, v35, v34
	v_add_f32_e32 v34, v63, v34
	v_add_f32_e32 v34, v62, v34
	v_cvt_pk_bf16_f32 v56, v56, v57
	v_cvt_pk_bf16_f32 v57, v58, v59
	v_add_f32_dpp v34, v34, v34 quad_perm:[1,0,3,2] row_mask:0xf bank_mask:0xf bound_ctrl:1
	global_store_dwordx4 v[72:73], v[54:57], off
	s_nop 0
	v_add_f32_dpp v34, v34, v34 quad_perm:[2,3,0,1] row_mask:0xf bank_mask:0xf bound_ctrl:1
	s_nop 1
	v_add_f32_dpp v34, v34, v34 row_half_mirror row_mask:0xf bank_mask:0xf bound_ctrl:1
	v_fmamk_f32 v34, v34, 0x3c800000, v64
	v_mul_f32_e32 v35, 0x4b800000, v34
	v_cmp_gt_f32_e64 s[4:5], s1, v34
	s_nop 1
	v_cndmask_b32_e64 v34, v34, v35, s[4:5]
	v_rsq_f32_e32 v34, v34
	s_nop 0
	v_mul_f32_e32 v35, 0x45800000, v34
	v_cndmask_b32_e64 v34, v34, v35, s[4:5]
	v_pk_mul_f32 v[32:33], v[34:35], v[32:33] op_sel_hi:[0,1]
	v_pk_mul_f32 v[54:55], v[34:35], v[74:75] op_sel_hi:[0,1]
	v_pk_mul_f32 v[56:57], v[6:7], v[32:33]
	v_pk_mul_f32 v[32:33], v[34:35], v[80:81] op_sel_hi:[0,1]
	v_pk_mul_f32 v[34:35], v[34:35], v[60:61] op_sel_hi:[0,1]
	v_pk_mul_f32 v[54:55], v[4:5], v[54:55]
	v_pk_mul_f32 v[32:33], v[0:1], v[32:33]
	v_pk_mul_f32 v[34:35], v[2:3], v[34:35] op_sel:[0,1] op_sel_hi:[1,0]
	v_cmp_gt_i32_e64 s[4:5], s19, v71
	s_and_saveexec_b64 s[12:13], s[4:5]
	s_cbranch_execz .LBB0_315
	v_mov_b32_e32 v58, v116
	v_mov_b32_e32 v59, v117
	v_mov_b32_e32 v60, v118
	v_mov_b32_e32 v61, v119
	v_mov_b32_e32 v72, v120
	v_mov_b32_e32 v73, v121
	v_mov_b32_e32 v74, v122
	v_mov_b32_e32 v75, v123
	v_mov_b32_e32 v76, v124
	v_mov_b32_e32 v77, v125
	v_mov_b32_e32 v78, v126
	v_mov_b32_e32 v79, v127
	v_mov_b32_e32 v80, v128
	v_mov_b32_e32 v81, v129
	v_mov_b32_e32 v82, v130
	v_mov_b32_e32 v83, v131
	v_mov_b32_e32 v62, v39
	v_mov_b32_e32 v63, v39
	v_mov_b32_e32 v84, v39
	v_mov_b32_e32 v85, v39
	v_mov_b32_e32 v86, v39
	v_mov_b32_e32 v87, v39
	v_mov_b32_e32 v88, v39
	v_mov_b32_e32 v89, v39
	v_mov_b32_dpp v62, v54 quad_perm:[2,3,0,1] row_mask:0xf bank_mask:0xf
	v_mov_b32_dpp v63, v55 quad_perm:[2,3,0,1] row_mask:0xf bank_mask:0xf
	v_mov_b32_dpp v84, v56 quad_perm:[2,3,0,1] row_mask:0xf bank_mask:0xf
	v_mov_b32_dpp v85, v57 quad_perm:[2,3,0,1] row_mask:0xf bank_mask:0xf
	v_mov_b32_dpp v86, v32 quad_perm:[2,3,0,1] row_mask:0xf bank_mask:0xf
	v_mov_b32_dpp v87, v33 quad_perm:[2,3,0,1] row_mask:0xf bank_mask:0xf
	v_mov_b32_dpp v88, v34 quad_perm:[2,3,0,1] row_mask:0xf bank_mask:0xf
	v_mov_b32_dpp v89, v35 quad_perm:[2,3,0,1] row_mask:0xf bank_mask:0xf
	v_mov_b32_e32 v91, v60
	v_mov_b32_e32 v60, v59
	v_mov_b32_e32 v59, v74
	v_mov_b32_e32 v74, v73
	v_mov_b32_e32 v73, v78
	v_mov_b32_e32 v78, v77
	v_mov_b32_e32 v77, v82
	v_mov_b32_e32 v82, v81
	v_pk_mul_f32 v[60:61], v[60:61], v[62:63]
	v_pk_mul_f32 v[62:63], v[74:75], v[84:85]
	v_pk_mul_f32 v[74:75], v[78:79], v[86:87]
	v_pk_mul_f32 v[78:79], v[82:83], v[88:89]
	v_mov_b32_e32 v90, v58
	v_mov_b32_e32 v58, v72
	v_mov_b32_e32 v72, v76
	v_mov_b32_e32 v76, v80
	v_cndmask_b32_e64 v61, v61, -v61, vcc
	v_cndmask_b32_e64 v60, v60, -v60, vcc
	v_cndmask_b32_e64 v63, v63, -v63, vcc
	v_cndmask_b32_e64 v62, v62, -v62, vcc
	v_cndmask_b32_e64 v75, v75, -v75, vcc
	v_cndmask_b32_e64 v74, v74, -v74, vcc
	v_cndmask_b32_e64 v79, v79, -v79, vcc
	v_cndmask_b32_e64 v78, v78, -v78, vcc
	v_pk_fma_f32 v[54:55], v[54:55], v[90:91], v[60:61]
	v_pk_fma_f32 v[56:57], v[56:57], v[58:59], v[62:63]
	v_pk_fma_f32 v[32:33], v[32:33], v[72:73], v[74:75]
	v_pk_fma_f32 v[34:35], v[34:35], v[76:77], v[78:79]
.LBB0_315:
	s_or_b64 exec, exec, s[12:13]
	v_lshlrev_b32_e32 v60, 16, v28
	v_and_b32_e32 v61, 0xffff0000, v28
	v_pk_mul_f32 v[62:63], v[60:61], v[60:61]
	v_lshlrev_b32_e32 v28, 16, v29
	v_and_b32_e32 v29, 0xffff0000, v29
	v_pk_mul_f32 v[72:73], v[28:29], v[28:29]
	v_add_f32_e32 v62, v62, v63
	v_lshlrev_b32_e32 v74, 16, v30
	v_and_b32_e32 v75, 0xffff0000, v30
	v_add_f32_e32 v62, v72, v62
	v_lshl_add_u64 v[58:59], v[52:53], 0, s[10:11]
	v_cvt_pk_bf16_f32 v53, v56, v57
	v_and_b32_e32 v56, 0xffff0000, v31
	v_lshlrev_b32_e32 v57, 16, v31
	v_pk_mul_f32 v[30:31], v[74:75], v[74:75]
	v_add_f32_e32 v62, v73, v62
	v_add_f32_e32 v30, v30, v62
	v_cvt_pk_bf16_f32 v52, v54, v55
	v_pk_mul_f32 v[54:55], v[56:57], v[56:57]
	v_add_f32_e32 v30, v31, v30
	v_add_f32_e32 v30, v55, v30
	v_add_f32_e32 v30, v54, v30
	v_cvt_pk_bf16_f32 v54, v32, v33
	v_cvt_pk_bf16_f32 v55, v34, v35
	v_add_f32_dpp v30, v30, v30 quad_perm:[1,0,3,2] row_mask:0xf bank_mask:0xf bound_ctrl:1
	global_store_dwordx4 v[58:59], v[52:55], off
	s_nop 0
	v_add_f32_dpp v30, v30, v30 quad_perm:[2,3,0,1] row_mask:0xf bank_mask:0xf bound_ctrl:1
	s_nop 1
	v_add_f32_dpp v30, v30, v30 row_half_mirror row_mask:0xf bank_mask:0xf bound_ctrl:1
	v_fmamk_f32 v30, v30, 0x3c800000, v64
	v_mul_f32_e32 v31, 0x4b800000, v30
	v_cmp_gt_f32_e64 s[4:5], s1, v30
	s_nop 1
	v_cndmask_b32_e64 v30, v30, v31, s[4:5]
	v_rsq_f32_e32 v30, v30
	s_nop 0
	v_mul_f32_e32 v31, 0x45800000, v30
	v_cndmask_b32_e64 v30, v30, v31, s[4:5]
	v_pk_mul_f32 v[28:29], v[30:31], v[28:29] op_sel_hi:[0,1]
	v_pk_mul_f32 v[32:33], v[30:31], v[60:61] op_sel_hi:[0,1]
	v_pk_mul_f32 v[34:35], v[6:7], v[28:29]
	v_pk_mul_f32 v[28:29], v[30:31], v[74:75] op_sel_hi:[0,1]
	v_pk_mul_f32 v[30:31], v[30:31], v[56:57] op_sel_hi:[0,1]
	v_pk_mul_f32 v[32:33], v[4:5], v[32:33]
	v_pk_mul_f32 v[28:29], v[0:1], v[28:29]
	v_pk_mul_f32 v[30:31], v[2:3], v[30:31] op_sel:[0,1] op_sel_hi:[1,0]
	v_cmp_gt_i32_e64 s[4:5], s19, v70
	s_and_saveexec_b64 s[12:13], s[4:5]
	s_cbranch_execz .LBB0_317
	v_mov_b32_e32 v52, v132
	v_mov_b32_e32 v53, v133
	v_mov_b32_e32 v54, v134
	v_mov_b32_e32 v55, v135
	v_mov_b32_e32 v56, v136
	v_mov_b32_e32 v57, v137
	v_mov_b32_e32 v58, v138
	v_mov_b32_e32 v59, v139
	v_mov_b32_e32 v60, v140
	v_mov_b32_e32 v61, v141
	v_mov_b32_e32 v62, v142
	v_mov_b32_e32 v63, v143
	v_mov_b32_e32 v70, v144
	v_mov_b32_e32 v71, v145
	v_mov_b32_e32 v72, v146
	v_mov_b32_e32 v73, v147
	v_mov_b32_e32 v74, v39
	v_mov_b32_e32 v75, v39
	v_mov_b32_e32 v76, v39
	v_mov_b32_e32 v77, v39
	v_mov_b32_e32 v78, v39
	v_mov_b32_e32 v79, v39
	v_mov_b32_e32 v80, v39
	v_mov_b32_e32 v81, v39
	v_mov_b32_dpp v74, v32 quad_perm:[2,3,0,1] row_mask:0xf bank_mask:0xf
	v_mov_b32_dpp v75, v33 quad_perm:[2,3,0,1] row_mask:0xf bank_mask:0xf
	v_mov_b32_dpp v76, v34 quad_perm:[2,3,0,1] row_mask:0xf bank_mask:0xf
	v_mov_b32_dpp v77, v35 quad_perm:[2,3,0,1] row_mask:0xf bank_mask:0xf
	v_mov_b32_dpp v78, v28 quad_perm:[2,3,0,1] row_mask:0xf bank_mask:0xf
	v_mov_b32_dpp v79, v29 quad_perm:[2,3,0,1] row_mask:0xf bank_mask:0xf
	v_mov_b32_dpp v80, v30 quad_perm:[2,3,0,1] row_mask:0xf bank_mask:0xf
	v_mov_b32_dpp v81, v31 quad_perm:[2,3,0,1] row_mask:0xf bank_mask:0xf
	v_mov_b32_e32 v83, v54
	v_mov_b32_e32 v54, v53
	v_mov_b32_e32 v53, v58
	v_mov_b32_e32 v58, v57
	v_mov_b32_e32 v57, v62
	v_mov_b32_e32 v62, v61
	v_mov_b32_e32 v61, v72
	v_mov_b32_e32 v72, v71
	v_mov_b32_e32 v82, v52
	v_mov_b32_e32 v52, v56
	v_mov_b32_e32 v56, v60
	v_mov_b32_e32 v60, v70
	v_pk_mul_f32 v[54:55], v[54:55], v[74:75]
	v_pk_mul_f32 v[58:59], v[58:59], v[76:77]
	v_pk_mul_f32 v[62:63], v[62:63], v[78:79]
	v_pk_mul_f32 v[70:71], v[72:73], v[80:81]
	v_cndmask_b32_e64 v55, v55, -v55, vcc
	v_cndmask_b32_e64 v54, v54, -v54, vcc
	v_cndmask_b32_e64 v59, v59, -v59, vcc
	v_cndmask_b32_e64 v58, v58, -v58, vcc
	v_cndmask_b32_e64 v63, v63, -v63, vcc
	v_cndmask_b32_e64 v62, v62, -v62, vcc
	v_cndmask_b32_e64 v71, v71, -v71, vcc
	v_cndmask_b32_e64 v70, v70, -v70, vcc
	v_pk_fma_f32 v[32:33], v[32:33], v[82:83], v[54:55]
	v_pk_fma_f32 v[34:35], v[34:35], v[52:53], v[58:59]
	v_pk_fma_f32 v[28:29], v[28:29], v[56:57], v[62:63]
	v_pk_fma_f32 v[30:31], v[30:31], v[60:61], v[70:71]
.LBB0_317:
	s_or_b64 exec, exec, s[12:13]
	v_lshlrev_b32_e32 v54, 16, v24
	v_and_b32_e32 v55, 0xffff0000, v24
	v_pk_mul_f32 v[56:57], v[54:55], v[54:55]
	v_lshlrev_b32_e32 v24, 16, v25
	v_and_b32_e32 v25, 0xffff0000, v25
	v_pk_mul_f32 v[58:59], v[24:25], v[24:25]
	v_add_f32_e32 v56, v56, v57
	v_lshlrev_b32_e32 v60, 16, v26
	v_and_b32_e32 v61, 0xffff0000, v26
	v_add_f32_e32 v56, v58, v56
	v_and_b32_e32 v52, 0xffff0000, v27
	v_lshlrev_b32_e32 v53, 16, v27
	v_pk_mul_f32 v[26:27], v[60:61], v[60:61]
	v_add_f32_e32 v56, v59, v56
	v_add_f32_e32 v26, v26, v56
	v_cvt_pk_bf16_f32 v32, v32, v33
	v_cvt_pk_bf16_f32 v33, v34, v35
	v_pk_mul_f32 v[34:35], v[52:53], v[52:53]
	v_add_f32_e32 v26, v27, v26
	v_add_f32_e32 v26, v35, v26
	v_add_f32_e32 v26, v34, v26
	v_cvt_pk_bf16_f32 v34, v28, v29
	v_cvt_pk_bf16_f32 v35, v30, v31
	v_add_f32_dpp v26, v26, v26 quad_perm:[1,0,3,2] row_mask:0xf bank_mask:0xf bound_ctrl:1
	v_lshl_add_u64 v[50:51], v[50:51], 0, s[10:11]
	global_store_dwordx4 v[50:51], v[32:35], off
	v_add_f32_dpp v26, v26, v26 quad_perm:[2,3,0,1] row_mask:0xf bank_mask:0xf bound_ctrl:1
	s_nop 1
	v_add_f32_dpp v26, v26, v26 row_half_mirror row_mask:0xf bank_mask:0xf bound_ctrl:1
	v_fmamk_f32 v26, v26, 0x3c800000, v64
	v_mul_f32_e32 v27, 0x4b800000, v26
	v_cmp_gt_f32_e64 s[4:5], s1, v26
	s_nop 1
	v_cndmask_b32_e64 v26, v26, v27, s[4:5]
	v_rsq_f32_e32 v26, v26
	s_nop 0
	v_mul_f32_e32 v27, 0x45800000, v26
	v_cndmask_b32_e64 v26, v26, v27, s[4:5]
	v_pk_mul_f32 v[24:25], v[26:27], v[24:25] op_sel_hi:[0,1]
	v_pk_mul_f32 v[28:29], v[26:27], v[54:55] op_sel_hi:[0,1]
	v_pk_mul_f32 v[30:31], v[6:7], v[24:25]
	v_pk_mul_f32 v[24:25], v[26:27], v[60:61] op_sel_hi:[0,1]
	v_pk_mul_f32 v[26:27], v[26:27], v[52:53] op_sel_hi:[0,1]
	v_pk_mul_f32 v[28:29], v[4:5], v[28:29]
	v_pk_mul_f32 v[24:25], v[0:1], v[24:25]
	v_pk_mul_f32 v[26:27], v[2:3], v[26:27] op_sel:[0,1] op_sel_hi:[1,0]
	v_cmp_gt_i32_e64 s[4:5], s19, v69
	s_and_saveexec_b64 s[12:13], s[4:5]
	s_cbranch_execz .LBB0_319
	v_mov_b32_e32 v32, v148
	v_mov_b32_e32 v33, v149
	v_mov_b32_e32 v34, v150
	v_mov_b32_e32 v35, v151
	v_mov_b32_e32 v50, v152
	v_mov_b32_e32 v51, v153
	v_mov_b32_e32 v52, v154
	v_mov_b32_e32 v53, v155
	v_mov_b32_e32 v54, v156
	v_mov_b32_e32 v55, v157
	v_mov_b32_e32 v56, v158
	v_mov_b32_e32 v57, v159
	v_mov_b32_e32 v58, v160
	v_mov_b32_e32 v59, v161
	v_mov_b32_e32 v60, v162
	v_mov_b32_e32 v61, v163
	v_mov_b32_e32 v62, v39
	v_mov_b32_e32 v63, v39
	v_mov_b32_e32 v70, v39
	v_mov_b32_e32 v71, v39
	v_mov_b32_e32 v72, v39
	v_mov_b32_e32 v73, v39
	v_mov_b32_e32 v74, v39
	v_mov_b32_e32 v75, v39
	v_mov_b32_dpp v62, v28 quad_perm:[2,3,0,1] row_mask:0xf bank_mask:0xf
	v_mov_b32_dpp v63, v29 quad_perm:[2,3,0,1] row_mask:0xf bank_mask:0xf
	v_mov_b32_dpp v70, v30 quad_perm:[2,3,0,1] row_mask:0xf bank_mask:0xf
	v_mov_b32_dpp v71, v31 quad_perm:[2,3,0,1] row_mask:0xf bank_mask:0xf
	v_mov_b32_dpp v72, v24 quad_perm:[2,3,0,1] row_mask:0xf bank_mask:0xf
	v_mov_b32_dpp v73, v25 quad_perm:[2,3,0,1] row_mask:0xf bank_mask:0xf
	v_mov_b32_dpp v74, v26 quad_perm:[2,3,0,1] row_mask:0xf bank_mask:0xf
	v_mov_b32_dpp v75, v27 quad_perm:[2,3,0,1] row_mask:0xf bank_mask:0xf
	v_mov_b32_e32 v77, v34
	v_mov_b32_e32 v34, v33
	v_mov_b32_e32 v33, v52
	v_mov_b32_e32 v52, v51
	v_mov_b32_e32 v51, v56
	v_mov_b32_e32 v56, v55
	v_mov_b32_e32 v55, v60
	v_mov_b32_e32 v60, v59
	v_mov_b32_e32 v76, v32
	v_mov_b32_e32 v32, v50
	v_mov_b32_e32 v50, v54
	v_mov_b32_e32 v54, v58
	v_pk_mul_f32 v[34:35], v[34:35], v[62:63]
	v_pk_mul_f32 v[52:53], v[52:53], v[70:71]
	v_pk_mul_f32 v[56:57], v[56:57], v[72:73]
	v_pk_mul_f32 v[58:59], v[60:61], v[74:75]
	v_cndmask_b32_e64 v35, v35, -v35, vcc
	v_cndmask_b32_e64 v34, v34, -v34, vcc
	v_cndmask_b32_e64 v53, v53, -v53, vcc
	v_cndmask_b32_e64 v52, v52, -v52, vcc
	v_cndmask_b32_e64 v57, v57, -v57, vcc
	v_cndmask_b32_e64 v56, v56, -v56, vcc
	v_cndmask_b32_e64 v59, v59, -v59, vcc
	v_cndmask_b32_e64 v58, v58, -v58, vcc
	v_pk_fma_f32 v[28:29], v[28:29], v[76:77], v[34:35]
	v_pk_fma_f32 v[30:31], v[30:31], v[32:33], v[52:53]
	v_pk_fma_f32 v[24:25], v[24:25], v[50:51], v[56:57]
	v_pk_fma_f32 v[26:27], v[26:27], v[54:55], v[58:59]
.LBB0_319:
	s_or_b64 exec, exec, s[12:13]
	v_lshl_add_u64 v[32:33], v[48:49], 0, s[10:11]
	v_lshlrev_b32_e32 v48, 16, v20
	v_and_b32_e32 v49, 0xffff0000, v20
	v_pk_mul_f32 v[50:51], v[48:49], v[48:49]
	v_lshlrev_b32_e32 v20, 16, v21
	v_and_b32_e32 v21, 0xffff0000, v21
	v_pk_mul_f32 v[52:53], v[20:21], v[20:21]
	v_add_f32_e32 v50, v50, v51
	v_lshlrev_b32_e32 v54, 16, v22
	v_and_b32_e32 v55, 0xffff0000, v22
	v_add_f32_e32 v50, v52, v50
	v_and_b32_e32 v34, 0xffff0000, v23
	v_lshlrev_b32_e32 v35, 16, v23
	v_pk_mul_f32 v[22:23], v[54:55], v[54:55]
	v_add_f32_e32 v50, v53, v50
	v_add_f32_e32 v22, v22, v50
	v_cvt_pk_bf16_f32 v28, v28, v29
	v_cvt_pk_bf16_f32 v29, v30, v31
	v_pk_mul_f32 v[30:31], v[34:35], v[34:35]
	v_add_f32_e32 v22, v23, v22
	v_add_f32_e32 v22, v31, v22
	v_add_f32_e32 v22, v30, v22
	v_cvt_pk_bf16_f32 v30, v24, v25
	v_cvt_pk_bf16_f32 v31, v26, v27
	v_add_f32_dpp v22, v22, v22 quad_perm:[1,0,3,2] row_mask:0xf bank_mask:0xf bound_ctrl:1
	global_store_dwordx4 v[32:33], v[28:31], off
	s_nop 0
	v_add_f32_dpp v22, v22, v22 quad_perm:[2,3,0,1] row_mask:0xf bank_mask:0xf bound_ctrl:1
	s_nop 1
	v_add_f32_dpp v22, v22, v22 row_half_mirror row_mask:0xf bank_mask:0xf bound_ctrl:1
	v_fmamk_f32 v22, v22, 0x3c800000, v64
	v_mul_f32_e32 v23, 0x4b800000, v22
	v_cmp_gt_f32_e64 s[4:5], s1, v22
	s_nop 1
	v_cndmask_b32_e64 v22, v22, v23, s[4:5]
	v_rsq_f32_e32 v22, v22
	s_nop 0
	v_mul_f32_e32 v23, 0x45800000, v22
	v_cndmask_b32_e64 v22, v22, v23, s[4:5]
	v_pk_mul_f32 v[20:21], v[22:23], v[20:21] op_sel_hi:[0,1]
	v_pk_mul_f32 v[24:25], v[22:23], v[48:49] op_sel_hi:[0,1]
	v_pk_mul_f32 v[26:27], v[6:7], v[20:21]
	v_pk_mul_f32 v[20:21], v[22:23], v[54:55] op_sel_hi:[0,1]
	v_pk_mul_f32 v[22:23], v[22:23], v[34:35] op_sel_hi:[0,1]
	v_pk_mul_f32 v[24:25], v[4:5], v[24:25]
	v_pk_mul_f32 v[20:21], v[0:1], v[20:21]
	v_pk_mul_f32 v[22:23], v[2:3], v[22:23] op_sel:[0,1] op_sel_hi:[1,0]
	v_cmp_gt_i32_e64 s[4:5], s19, v68
	s_and_saveexec_b64 s[12:13], s[4:5]
	s_cbranch_execz .LBB0_321
	v_mov_b32_e32 v28, v164
	v_mov_b32_e32 v29, v165
	v_mov_b32_e32 v30, v166
	v_mov_b32_e32 v31, v167
	v_mov_b32_e32 v32, v168
	v_mov_b32_e32 v33, v169
	v_mov_b32_e32 v34, v170
	v_mov_b32_e32 v35, v171
	v_mov_b32_e32 v48, v172
	v_mov_b32_e32 v49, v173
	v_mov_b32_e32 v50, v174
	v_mov_b32_e32 v51, v175
	v_mov_b32_e32 v52, v176
	v_mov_b32_e32 v53, v177
	v_mov_b32_e32 v54, v178
	v_mov_b32_e32 v55, v179
	v_mov_b32_e32 v56, v39
	v_mov_b32_e32 v57, v39
	v_mov_b32_e32 v58, v39
	v_mov_b32_e32 v59, v39
	v_mov_b32_e32 v60, v39
	v_mov_b32_e32 v61, v39
	v_mov_b32_e32 v62, v39
	v_mov_b32_e32 v63, v39
	v_mov_b32_dpp v56, v24 quad_perm:[2,3,0,1] row_mask:0xf bank_mask:0xf
	v_mov_b32_dpp v57, v25 quad_perm:[2,3,0,1] row_mask:0xf bank_mask:0xf
	v_mov_b32_dpp v58, v26 quad_perm:[2,3,0,1] row_mask:0xf bank_mask:0xf
	v_mov_b32_dpp v59, v27 quad_perm:[2,3,0,1] row_mask:0xf bank_mask:0xf
	v_mov_b32_dpp v60, v20 quad_perm:[2,3,0,1] row_mask:0xf bank_mask:0xf
	v_mov_b32_dpp v61, v21 quad_perm:[2,3,0,1] row_mask:0xf bank_mask:0xf
	v_mov_b32_dpp v62, v22 quad_perm:[2,3,0,1] row_mask:0xf bank_mask:0xf
	v_mov_b32_dpp v63, v23 quad_perm:[2,3,0,1] row_mask:0xf bank_mask:0xf
	v_mov_b32_e32 v69, v30
	v_mov_b32_e32 v30, v29
	v_mov_b32_e32 v29, v34
	v_mov_b32_e32 v34, v33
	v_mov_b32_e32 v33, v50
	v_mov_b32_e32 v50, v49
	v_mov_b32_e32 v49, v54
	v_mov_b32_e32 v54, v53
	v_mov_b32_e32 v68, v28
	v_mov_b32_e32 v28, v32
	v_mov_b32_e32 v32, v48
	v_mov_b32_e32 v48, v52
	v_pk_mul_f32 v[30:31], v[30:31], v[56:57]
	v_pk_mul_f32 v[34:35], v[34:35], v[58:59]
	v_pk_mul_f32 v[50:51], v[50:51], v[60:61]
	v_pk_mul_f32 v[52:53], v[54:55], v[62:63]
	v_cndmask_b32_e64 v31, v31, -v31, vcc
	v_cndmask_b32_e64 v30, v30, -v30, vcc
	v_cndmask_b32_e64 v35, v35, -v35, vcc
	v_cndmask_b32_e64 v34, v34, -v34, vcc
	v_cndmask_b32_e64 v51, v51, -v51, vcc
	v_cndmask_b32_e64 v50, v50, -v50, vcc
	v_cndmask_b32_e64 v53, v53, -v53, vcc
	v_cndmask_b32_e64 v52, v52, -v52, vcc
	v_pk_fma_f32 v[24:25], v[24:25], v[68:69], v[30:31]
	v_pk_fma_f32 v[26:27], v[26:27], v[28:29], v[34:35]
	v_pk_fma_f32 v[20:21], v[20:21], v[32:33], v[50:51]
	v_pk_fma_f32 v[22:23], v[22:23], v[48:49], v[52:53]
.LBB0_321:
	s_or_b64 exec, exec, s[12:13]
	v_lshlrev_b32_e32 v32, 16, v16
	v_and_b32_e32 v33, 0xffff0000, v16
	v_pk_mul_f32 v[34:35], v[32:33], v[32:33]
	v_lshlrev_b32_e32 v16, 16, v17
	v_and_b32_e32 v17, 0xffff0000, v17
	v_lshl_add_u64 v[28:29], v[46:47], 0, s[10:11]
	v_pk_mul_f32 v[46:47], v[16:17], v[16:17]
	v_add_f32_e32 v34, v34, v35
	v_lshlrev_b32_e32 v48, 16, v18
	v_and_b32_e32 v49, 0xffff0000, v18
	v_add_f32_e32 v34, v46, v34
	v_and_b32_e32 v30, 0xffff0000, v19
	v_lshlrev_b32_e32 v31, 16, v19
	v_pk_mul_f32 v[18:19], v[48:49], v[48:49]
	v_add_f32_e32 v34, v47, v34
	v_add_f32_e32 v18, v18, v34
	v_cvt_pk_bf16_f32 v24, v24, v25
	v_cvt_pk_bf16_f32 v25, v26, v27
	v_pk_mul_f32 v[26:27], v[30:31], v[30:31]
	v_add_f32_e32 v18, v19, v18
	v_add_f32_e32 v18, v27, v18
	v_add_f32_e32 v18, v26, v18
	v_cvt_pk_bf16_f32 v26, v20, v21
	v_cvt_pk_bf16_f32 v27, v22, v23
	v_add_f32_dpp v18, v18, v18 quad_perm:[1,0,3,2] row_mask:0xf bank_mask:0xf bound_ctrl:1
	global_store_dwordx4 v[28:29], v[24:27], off
	s_nop 0
	v_add_f32_dpp v18, v18, v18 quad_perm:[2,3,0,1] row_mask:0xf bank_mask:0xf bound_ctrl:1
	s_nop 1
	v_add_f32_dpp v18, v18, v18 row_half_mirror row_mask:0xf bank_mask:0xf bound_ctrl:1
	v_fmamk_f32 v18, v18, 0x3c800000, v64
	v_mul_f32_e32 v19, 0x4b800000, v18
	v_cmp_gt_f32_e64 s[4:5], s1, v18
	s_nop 1
	v_cndmask_b32_e64 v18, v18, v19, s[4:5]
	v_rsq_f32_e32 v18, v18
	s_nop 0
	v_mul_f32_e32 v19, 0x45800000, v18
	v_cndmask_b32_e64 v18, v18, v19, s[4:5]
	v_pk_mul_f32 v[16:17], v[18:19], v[16:17] op_sel_hi:[0,1]
	v_pk_mul_f32 v[20:21], v[18:19], v[32:33] op_sel_hi:[0,1]
	v_pk_mul_f32 v[22:23], v[6:7], v[16:17]
	v_pk_mul_f32 v[16:17], v[18:19], v[48:49] op_sel_hi:[0,1]
	v_pk_mul_f32 v[18:19], v[18:19], v[30:31] op_sel_hi:[0,1]
	v_pk_mul_f32 v[20:21], v[4:5], v[20:21]
	v_pk_mul_f32 v[16:17], v[0:1], v[16:17]
	v_pk_mul_f32 v[18:19], v[2:3], v[18:19] op_sel:[0,1] op_sel_hi:[1,0]
	v_cmp_gt_i32_e64 s[4:5], s19, v67
	s_and_saveexec_b64 s[12:13], s[4:5]
	s_cbranch_execz .LBB0_323
	v_mov_b32_e32 v24, v180
	v_mov_b32_e32 v25, v181
	v_mov_b32_e32 v26, v182
	v_mov_b32_e32 v27, v183
	v_mov_b32_e32 v28, v184
	v_mov_b32_e32 v29, v185
	v_mov_b32_e32 v30, v186
	v_mov_b32_e32 v31, v187
	v_mov_b32_e32 v32, v192
	v_mov_b32_e32 v33, v193
	v_mov_b32_e32 v34, v194
	v_mov_b32_e32 v35, v195
	v_mov_b32_e32 v46, v196
	v_mov_b32_e32 v47, v197
	v_mov_b32_e32 v48, v198
	v_mov_b32_e32 v49, v199
	v_mov_b32_e32 v50, v39
	v_mov_b32_e32 v51, v39
	v_mov_b32_e32 v52, v39
	v_mov_b32_e32 v53, v39
	v_mov_b32_e32 v54, v39
	v_mov_b32_e32 v55, v39
	v_mov_b32_e32 v56, v39
	v_mov_b32_e32 v57, v39
	v_mov_b32_dpp v50, v20 quad_perm:[2,3,0,1] row_mask:0xf bank_mask:0xf
	v_mov_b32_dpp v51, v21 quad_perm:[2,3,0,1] row_mask:0xf bank_mask:0xf
	v_mov_b32_dpp v52, v22 quad_perm:[2,3,0,1] row_mask:0xf bank_mask:0xf
	v_mov_b32_dpp v53, v23 quad_perm:[2,3,0,1] row_mask:0xf bank_mask:0xf
	v_mov_b32_dpp v54, v16 quad_perm:[2,3,0,1] row_mask:0xf bank_mask:0xf
	v_mov_b32_dpp v55, v17 quad_perm:[2,3,0,1] row_mask:0xf bank_mask:0xf
	v_mov_b32_dpp v56, v18 quad_perm:[2,3,0,1] row_mask:0xf bank_mask:0xf
	v_mov_b32_dpp v57, v19 quad_perm:[2,3,0,1] row_mask:0xf bank_mask:0xf
	v_mov_b32_e32 v59, v26
	v_mov_b32_e32 v26, v25
	v_mov_b32_e32 v25, v30
	v_mov_b32_e32 v30, v29
	v_mov_b32_e32 v29, v34
	v_mov_b32_e32 v34, v33
	v_mov_b32_e32 v33, v48
	v_mov_b32_e32 v48, v47
	v_mov_b32_e32 v58, v24
	v_mov_b32_e32 v24, v28
	v_mov_b32_e32 v28, v32
	v_mov_b32_e32 v32, v46
	v_pk_mul_f32 v[26:27], v[26:27], v[50:51]
	v_pk_mul_f32 v[30:31], v[30:31], v[52:53]
	v_pk_mul_f32 v[34:35], v[34:35], v[54:55]
	v_pk_mul_f32 v[46:47], v[48:49], v[56:57]
	v_cndmask_b32_e64 v27, v27, -v27, vcc
	v_cndmask_b32_e64 v26, v26, -v26, vcc
	v_cndmask_b32_e64 v31, v31, -v31, vcc
	v_cndmask_b32_e64 v30, v30, -v30, vcc
	v_cndmask_b32_e64 v35, v35, -v35, vcc
	v_cndmask_b32_e64 v34, v34, -v34, vcc
	v_cndmask_b32_e64 v47, v47, -v47, vcc
	v_cndmask_b32_e64 v46, v46, -v46, vcc
	v_pk_fma_f32 v[20:21], v[20:21], v[58:59], v[26:27]
	v_pk_fma_f32 v[22:23], v[22:23], v[24:25], v[30:31]
	v_pk_fma_f32 v[16:17], v[16:17], v[28:29], v[34:35]
	v_pk_fma_f32 v[18:19], v[18:19], v[32:33], v[46:47]
.LBB0_323:
	s_or_b64 exec, exec, s[12:13]
	v_lshlrev_b32_e32 v28, 16, v12
	v_and_b32_e32 v29, 0xffff0000, v12
	v_pk_mul_f32 v[30:31], v[28:29], v[28:29]
	v_lshlrev_b32_e32 v12, 16, v13
	v_and_b32_e32 v13, 0xffff0000, v13
	v_pk_mul_f32 v[32:33], v[12:13], v[12:13]
	v_add_f32_e32 v30, v30, v31
	v_lshlrev_b32_e32 v34, 16, v14
	v_and_b32_e32 v35, 0xffff0000, v14
	v_add_f32_e32 v30, v32, v30
	v_and_b32_e32 v26, 0xffff0000, v15
	v_lshlrev_b32_e32 v27, 16, v15
	v_pk_mul_f32 v[14:15], v[34:35], v[34:35]
	v_add_f32_e32 v30, v33, v30
	v_add_f32_e32 v14, v14, v30
	v_cvt_pk_bf16_f32 v20, v20, v21
	v_cvt_pk_bf16_f32 v21, v22, v23
	v_pk_mul_f32 v[22:23], v[26:27], v[26:27]
	v_add_f32_e32 v14, v15, v14
	v_add_f32_e32 v14, v23, v14
	v_add_f32_e32 v14, v22, v14
	v_cvt_pk_bf16_f32 v22, v16, v17
	v_cvt_pk_bf16_f32 v23, v18, v19
	v_add_f32_dpp v14, v14, v14 quad_perm:[1,0,3,2] row_mask:0xf bank_mask:0xf bound_ctrl:1
	v_lshl_add_u64 v[24:25], v[44:45], 0, s[10:11]
	global_store_dwordx4 v[24:25], v[20:23], off
	v_add_f32_dpp v14, v14, v14 quad_perm:[2,3,0,1] row_mask:0xf bank_mask:0xf bound_ctrl:1
	s_nop 1
	v_add_f32_dpp v14, v14, v14 row_half_mirror row_mask:0xf bank_mask:0xf bound_ctrl:1
	v_fmamk_f32 v14, v14, 0x3c800000, v64
	v_mul_f32_e32 v15, 0x4b800000, v14
	v_cmp_gt_f32_e64 s[4:5], s1, v14
	s_nop 1
	v_cndmask_b32_e64 v14, v14, v15, s[4:5]
	v_rsq_f32_e32 v14, v14
	s_nop 0
	v_mul_f32_e32 v15, 0x45800000, v14
	v_cndmask_b32_e64 v14, v14, v15, s[4:5]
	v_pk_mul_f32 v[12:13], v[14:15], v[12:13] op_sel_hi:[0,1]
	v_pk_mul_f32 v[16:17], v[14:15], v[28:29] op_sel_hi:[0,1]
	v_pk_mul_f32 v[18:19], v[6:7], v[12:13]
	v_pk_mul_f32 v[12:13], v[14:15], v[34:35] op_sel_hi:[0,1]
	v_pk_mul_f32 v[14:15], v[14:15], v[26:27] op_sel_hi:[0,1]
	v_pk_mul_f32 v[16:17], v[4:5], v[16:17]
	v_pk_mul_f32 v[12:13], v[0:1], v[12:13]
	v_pk_mul_f32 v[14:15], v[2:3], v[14:15] op_sel:[0,1] op_sel_hi:[1,0]
	v_cmp_gt_i32_e64 s[4:5], s19, v66
	s_and_saveexec_b64 s[12:13], s[4:5]
	s_cbranch_execz .LBB0_325
	v_mov_b32_e32 v20, v200
	v_mov_b32_e32 v21, v201
	v_mov_b32_e32 v22, v202
	v_mov_b32_e32 v23, v203
	v_mov_b32_e32 v24, v204
	v_mov_b32_e32 v25, v205
	v_mov_b32_e32 v26, v206
	v_mov_b32_e32 v27, v207
	v_mov_b32_e32 v28, v208
	v_mov_b32_e32 v29, v209
	v_mov_b32_e32 v30, v210
	v_mov_b32_e32 v31, v211
	v_mov_b32_e32 v32, v212
	v_mov_b32_e32 v33, v213
	v_mov_b32_e32 v34, v214
	v_mov_b32_e32 v35, v215
	v_mov_b32_e32 v44, v39
	v_mov_b32_e32 v45, v39
	v_mov_b32_e32 v46, v39
	v_mov_b32_e32 v47, v39
	v_mov_b32_e32 v48, v39
	v_mov_b32_e32 v49, v39
	v_mov_b32_e32 v50, v39
	v_mov_b32_e32 v51, v39
	v_mov_b32_dpp v44, v16 quad_perm:[2,3,0,1] row_mask:0xf bank_mask:0xf
	v_mov_b32_dpp v45, v17 quad_perm:[2,3,0,1] row_mask:0xf bank_mask:0xf
	v_mov_b32_dpp v46, v18 quad_perm:[2,3,0,1] row_mask:0xf bank_mask:0xf
	v_mov_b32_dpp v47, v19 quad_perm:[2,3,0,1] row_mask:0xf bank_mask:0xf
	v_mov_b32_dpp v48, v12 quad_perm:[2,3,0,1] row_mask:0xf bank_mask:0xf
	v_mov_b32_dpp v49, v13 quad_perm:[2,3,0,1] row_mask:0xf bank_mask:0xf
	v_mov_b32_dpp v50, v14 quad_perm:[2,3,0,1] row_mask:0xf bank_mask:0xf
	v_mov_b32_dpp v51, v15 quad_perm:[2,3,0,1] row_mask:0xf bank_mask:0xf
	v_mov_b32_e32 v53, v22
	v_mov_b32_e32 v22, v21
	v_mov_b32_e32 v21, v26
	v_mov_b32_e32 v26, v25
	v_mov_b32_e32 v25, v30
	v_mov_b32_e32 v30, v29
	v_mov_b32_e32 v29, v34
	v_mov_b32_e32 v34, v33
	v_mov_b32_e32 v52, v20
	v_mov_b32_e32 v20, v24
	v_mov_b32_e32 v24, v28
	v_mov_b32_e32 v28, v32
	v_pk_mul_f32 v[22:23], v[22:23], v[44:45]
	v_pk_mul_f32 v[26:27], v[26:27], v[46:47]
	v_pk_mul_f32 v[30:31], v[30:31], v[48:49]
	v_pk_mul_f32 v[32:33], v[34:35], v[50:51]
	v_cndmask_b32_e64 v23, v23, -v23, vcc
	v_cndmask_b32_e64 v22, v22, -v22, vcc
	v_cndmask_b32_e64 v27, v27, -v27, vcc
	v_cndmask_b32_e64 v26, v26, -v26, vcc
	v_cndmask_b32_e64 v31, v31, -v31, vcc
	v_cndmask_b32_e64 v30, v30, -v30, vcc
	v_cndmask_b32_e64 v33, v33, -v33, vcc
	v_cndmask_b32_e64 v32, v32, -v32, vcc
	v_pk_fma_f32 v[16:17], v[16:17], v[52:53], v[22:23]
	v_pk_fma_f32 v[18:19], v[18:19], v[20:21], v[26:27]
	v_pk_fma_f32 v[12:13], v[12:13], v[24:25], v[30:31]
	v_pk_fma_f32 v[14:15], v[14:15], v[28:29], v[32:33]
.LBB0_325:
	s_or_b64 exec, exec, s[12:13]
	v_lshlrev_b32_e32 v24, 16, v8
	v_and_b32_e32 v25, 0xffff0000, v8
	v_pk_mul_f32 v[26:27], v[24:25], v[24:25]
	v_lshlrev_b32_e32 v8, 16, v9
	v_and_b32_e32 v9, 0xffff0000, v9
	v_pk_mul_f32 v[28:29], v[8:9], v[8:9]
	v_add_f32_e32 v26, v26, v27
	v_lshlrev_b32_e32 v30, 16, v10
	v_and_b32_e32 v31, 0xffff0000, v10
	v_add_f32_e32 v26, v28, v26
	v_and_b32_e32 v22, 0xffff0000, v11
	v_lshlrev_b32_e32 v23, 16, v11
	v_pk_mul_f32 v[10:11], v[30:31], v[30:31]
	v_add_f32_e32 v26, v29, v26
	v_add_f32_e32 v10, v10, v26
	v_cvt_pk_bf16_f32 v16, v16, v17
	v_cvt_pk_bf16_f32 v17, v18, v19
	v_pk_mul_f32 v[18:19], v[22:23], v[22:23]
	v_add_f32_e32 v10, v11, v10
	v_add_f32_e32 v10, v19, v10
	v_add_f32_e32 v10, v18, v10
	v_cvt_pk_bf16_f32 v18, v12, v13
	v_lshl_add_u64 v[20:21], v[42:43], 0, s[10:11]
	v_add_f32_dpp v10, v10, v10 quad_perm:[1,0,3,2] row_mask:0xf bank_mask:0xf bound_ctrl:1
	v_cvt_pk_bf16_f32 v19, v14, v15
	global_store_dwordx4 v[20:21], v[16:19], off
	v_add_f32_dpp v10, v10, v10 quad_perm:[2,3,0,1] row_mask:0xf bank_mask:0xf bound_ctrl:1
	s_nop 1
	v_add_f32_dpp v10, v10, v10 row_half_mirror row_mask:0xf bank_mask:0xf bound_ctrl:1
	v_fmamk_f32 v10, v10, 0x3c800000, v64
	v_mul_f32_e32 v11, 0x4b800000, v10
	v_cmp_gt_f32_e64 s[4:5], s1, v10
	s_nop 1
	v_cndmask_b32_e64 v10, v10, v11, s[4:5]
	v_rsq_f32_e32 v10, v10
	s_nop 0
	v_mul_f32_e32 v11, 0x45800000, v10
	v_cndmask_b32_e64 v10, v10, v11, s[4:5]
	v_pk_mul_f32 v[8:9], v[10:11], v[8:9] op_sel_hi:[0,1]
	v_pk_mul_f32 v[6:7], v[6:7], v[8:9]
	v_pk_mul_f32 v[8:9], v[10:11], v[30:31] op_sel_hi:[0,1]
	v_pk_mul_f32 v[12:13], v[10:11], v[24:25] op_sel_hi:[0,1]
	v_pk_mul_f32 v[0:1], v[0:1], v[8:9]
	v_pk_mul_f32 v[8:9], v[10:11], v[22:23] op_sel_hi:[0,1]
	v_pk_mul_f32 v[4:5], v[4:5], v[12:13]
	v_pk_mul_f32 v[2:3], v[2:3], v[8:9] op_sel:[0,1] op_sel_hi:[1,0]
	v_cmp_gt_i32_e64 s[4:5], s19, v65
	s_and_saveexec_b64 s[12:13], s[4:5]
	s_cbranch_execz .LBB0_310
	v_mov_b32_e32 v8, v216
	v_mov_b32_e32 v9, v217
	v_mov_b32_e32 v10, v218
	v_mov_b32_e32 v11, v219
	v_mov_b32_e32 v12, v220
	v_mov_b32_e32 v13, v221
	v_mov_b32_e32 v14, v222
	v_mov_b32_e32 v15, v223
	v_mov_b32_e32 v16, v224
	v_mov_b32_e32 v17, v225
	v_mov_b32_e32 v18, v226
	v_mov_b32_e32 v19, v227
	v_mov_b32_e32 v20, v228
	v_mov_b32_e32 v21, v229
	v_mov_b32_e32 v22, v230
	v_mov_b32_e32 v23, v231
	v_mov_b32_e32 v24, v39
	v_mov_b32_e32 v25, v39
	v_mov_b32_e32 v26, v39
	v_mov_b32_e32 v27, v39
	v_mov_b32_e32 v28, v39
	v_mov_b32_e32 v29, v39
	v_mov_b32_e32 v30, v39
	v_mov_b32_e32 v31, v39
	v_mov_b32_dpp v24, v4 quad_perm:[2,3,0,1] row_mask:0xf bank_mask:0xf
	v_mov_b32_dpp v25, v5 quad_perm:[2,3,0,1] row_mask:0xf bank_mask:0xf
	v_mov_b32_dpp v26, v6 quad_perm:[2,3,0,1] row_mask:0xf bank_mask:0xf
	v_mov_b32_dpp v27, v7 quad_perm:[2,3,0,1] row_mask:0xf bank_mask:0xf
	v_mov_b32_dpp v28, v0 quad_perm:[2,3,0,1] row_mask:0xf bank_mask:0xf
	v_mov_b32_dpp v29, v1 quad_perm:[2,3,0,1] row_mask:0xf bank_mask:0xf
	v_mov_b32_dpp v30, v2 quad_perm:[2,3,0,1] row_mask:0xf bank_mask:0xf
	v_mov_b32_dpp v31, v3 quad_perm:[2,3,0,1] row_mask:0xf bank_mask:0xf
	v_mov_b32_e32 v33, v10
	v_mov_b32_e32 v10, v9
	v_mov_b32_e32 v9, v14
	v_mov_b32_e32 v14, v13
	v_mov_b32_e32 v13, v18
	v_mov_b32_e32 v18, v17
	v_mov_b32_e32 v17, v22
	v_mov_b32_e32 v22, v21
	v_mov_b32_e32 v32, v8
	v_mov_b32_e32 v8, v12
	v_mov_b32_e32 v12, v16
	v_mov_b32_e32 v16, v20
	v_pk_mul_f32 v[10:11], v[10:11], v[24:25]
	v_pk_mul_f32 v[14:15], v[14:15], v[26:27]
	v_pk_mul_f32 v[18:19], v[18:19], v[28:29]
	v_pk_mul_f32 v[20:21], v[22:23], v[30:31]
	v_cndmask_b32_e64 v11, v11, -v11, vcc
	v_cndmask_b32_e64 v10, v10, -v10, vcc
	v_cndmask_b32_e64 v15, v15, -v15, vcc
	v_cndmask_b32_e64 v14, v14, -v14, vcc
	v_cndmask_b32_e64 v19, v19, -v19, vcc
	v_cndmask_b32_e64 v18, v18, -v18, vcc
	v_cndmask_b32_e64 v21, v21, -v21, vcc
	v_cndmask_b32_e64 v20, v20, -v20, vcc
	v_pk_fma_f32 v[4:5], v[4:5], v[32:33], v[10:11]
	v_pk_fma_f32 v[6:7], v[6:7], v[8:9], v[14:15]
	v_pk_fma_f32 v[0:1], v[0:1], v[12:13], v[18:19]
	v_pk_fma_f32 v[2:3], v[2:3], v[16:17], v[20:21]
	s_branch .LBB0_310
